# prologue: pe-bias sums pipelined 3 deep on the last waves; b_re/b_im rows batched
# speedup vs baseline: 1.0269x; 1.0097x over previous
; #define FIN(i) ((const float*)(const GAS float*)(((const float* const __attribute__((address_space(4)))*)__builtin_amdgcn_kernarg_segment_ptr())[i]))
; __device__ __forceinline__ void phase_prologue(Frame& F) {
;     ...
;     for (int it = F.gw; it < 64; it += F.ngw) {
;         const int l = it >> 5, j = (it >> 4) & 1, part = it & 15;
;         const float* pe = FIN(IN_PE) + ((size_t)(l * 2 + j) * 64 + part * 4) * 64;
;         const float* wp = FIN(IN_WPHI) + ((size_t)(l * 2 + j) * 64 + part * 4) * 4096;
;         float s = 0.f;
; #pragma unroll 16
;         for (int i = 0; i < 256; ++i) s += pe[i] * wp[(size_t)i * 64 + lane];
;         ((float*)(F.ws + WS_PEBP + l * al1m(SZ_PEBP)))[(j * 16 + part) * 64 + lane] = s;
;     }
.LBB0_69:
	s_sub_i32 s17, s88, s14
	s_add_i32 s17, s17, -1
	s_cmp_gt_i32 s17, 63
	v_mov_b32_e32 v69, 0
	s_cbranch_scc1 .LBB0_74
	s_load_dwordx4 s[8:11], s[0:1], 0x60
	s_add_u32 s12, s66, 0x9f00000
	s_addc_u32 s13, s67, 0
	s_lshl_b32 s15, s17, 2
	s_waitcnt lgkmcnt(0)
	v_lshl_add_u64 v[2:3], s[10:11], 0, v[68:69]
	s_mov_b64 s[4:5], 0x800
	s_lshl_b32 s16, s84, 5
	v_lshl_add_u64 v[2:3], v[2:3], 0, s[4:5]
	s_mov_b64 s[4:5], 0x1000
.LBB0_71:
	s_lshl_b32 s6, s15, 8
	s_and_b32 s20, s6, 0x3c00
	s_lshl_b32 s6, s15, 14
	s_and_b32 s21, s6, 0xf0000
	s_ashr_i32 s6, s17, 5
	s_bfe_u32 s7, s17, 0x10004
	s_lshl_b32 s10, s6, 1
	s_or_b32 s10, s10, s7
	s_ashr_i32 s11, s10, 31
	s_lshl_b64 s[18:19], s[10:11], 14
	s_or_b32 s7, s18, s20
	s_add_u32 s7, s8, s7
	s_addc_u32 s18, s9, s19
	s_lshl_b64 s[10:11], s[10:11], 20
	s_or_b32 s10, s10, s21
	v_lshl_add_u64 v[4:5], v[2:3], 0, s[10:11]
	v_mov_b32_e32 v6, 0
	s_mov_b32 s20, s7
	s_mov_b32 s21, s18
	global_load_dword v100, v[4:5], off offset:-2048
	global_load_dword v101, v[4:5], off offset:-1792
	global_load_dword v102, v[4:5], off offset:-1536
	global_load_dword v103, v[4:5], off offset:-1280
	global_load_dword v104, v[4:5], off offset:-1024
	global_load_dword v105, v[4:5], off offset:-768
	global_load_dword v106, v[4:5], off offset:-512
	global_load_dword v107, v[4:5], off offset:-256
	global_load_dword v108, v[4:5], off
	global_load_dword v109, v[4:5], off offset:256
	global_load_dword v110, v[4:5], off offset:512
	global_load_dword v111, v[4:5], off offset:768
	global_load_dword v112, v[4:5], off offset:1024
	global_load_dword v113, v[4:5], off offset:1280
	global_load_dword v114, v[4:5], off offset:1536
	global_load_dword v115, v[4:5], off offset:1792
	global_load_dwordx4 v[116:119], v69, s[20:21]
	global_load_dwordx4 v[120:123], v69, s[20:21] offset:16
	global_load_dwordx4 v[124:127], v69, s[20:21] offset:32
	global_load_dwordx4 v[128:131], v69, s[20:21] offset:48
	v_lshl_add_u64 v[4:5], v[4:5], 0, s[4:5]
	global_load_dword v132, v[4:5], off offset:-2048
	global_load_dword v133, v[4:5], off offset:-1792
	global_load_dword v134, v[4:5], off offset:-1536
	global_load_dword v135, v[4:5], off offset:-1280
	global_load_dword v136, v[4:5], off offset:-1024
	global_load_dword v137, v[4:5], off offset:-768
	global_load_dword v138, v[4:5], off offset:-512
	global_load_dword v139, v[4:5], off offset:-256
	global_load_dword v140, v[4:5], off
	global_load_dword v141, v[4:5], off offset:256
	global_load_dword v142, v[4:5], off offset:512
	global_load_dword v143, v[4:5], off offset:768
	global_load_dword v144, v[4:5], off offset:1024
	global_load_dword v145, v[4:5], off offset:1280
	global_load_dword v146, v[4:5], off offset:1536
	global_load_dword v147, v[4:5], off offset:1792
	global_load_dwordx4 v[148:151], v69, s[20:21] offset:64
	global_load_dwordx4 v[152:155], v69, s[20:21] offset:80
	global_load_dwordx4 v[156:159], v69, s[20:21] offset:96
	global_load_dwordx4 v[160:163], v69, s[20:21] offset:112
	v_lshl_add_u64 v[4:5], v[4:5], 0, s[4:5]
	global_load_dword v164, v[4:5], off offset:-2048
	global_load_dword v165, v[4:5], off offset:-1792
	global_load_dword v166, v[4:5], off offset:-1536
	global_load_dword v167, v[4:5], off offset:-1280
	global_load_dword v168, v[4:5], off offset:-1024
	global_load_dword v169, v[4:5], off offset:-768
	global_load_dword v170, v[4:5], off offset:-512
	global_load_dword v171, v[4:5], off offset:-256
	global_load_dword v172, v[4:5], off
	global_load_dword v173, v[4:5], off offset:256
	global_load_dword v174, v[4:5], off offset:512
	global_load_dword v175, v[4:5], off offset:768
	global_load_dword v176, v[4:5], off offset:1024
	global_load_dword v177, v[4:5], off offset:1280
	global_load_dword v178, v[4:5], off offset:1536
	global_load_dword v179, v[4:5], off offset:1792
	global_load_dwordx4 v[180:183], v69, s[20:21] offset:128
	global_load_dwordx4 v[184:187], v69, s[20:21] offset:144
	global_load_dwordx4 v[188:191], v69, s[20:21] offset:160
	global_load_dwordx4 v[192:195], v69, s[20:21] offset:176
	v_lshl_add_u64 v[4:5], v[4:5], 0, s[4:5]
	s_waitcnt vmcnt(40)
	v_fmac_f32_e32 v6, v116, v100
	v_fmac_f32_e32 v6, v117, v101
	v_fmac_f32_e32 v6, v118, v102
	v_fmac_f32_e32 v6, v119, v103
	v_fmac_f32_e32 v6, v120, v104
	v_fmac_f32_e32 v6, v121, v105
	v_fmac_f32_e32 v6, v122, v106
	v_fmac_f32_e32 v6, v123, v107
	v_fmac_f32_e32 v6, v124, v108
	v_fmac_f32_e32 v6, v125, v109
	v_fmac_f32_e32 v6, v126, v110
	v_fmac_f32_e32 v6, v127, v111
	v_fmac_f32_e32 v6, v128, v112
	v_fmac_f32_e32 v6, v129, v113
	v_fmac_f32_e32 v6, v130, v114
	v_fmac_f32_e32 v6, v131, v115
	global_load_dword v100, v[4:5], off offset:-2048
	global_load_dword v101, v[4:5], off offset:-1792
	global_load_dword v102, v[4:5], off offset:-1536
	global_load_dword v103, v[4:5], off offset:-1280
	global_load_dword v104, v[4:5], off offset:-1024
	global_load_dword v105, v[4:5], off offset:-768
	global_load_dword v106, v[4:5], off offset:-512
	global_load_dword v107, v[4:5], off offset:-256
	global_load_dword v108, v[4:5], off
	global_load_dword v109, v[4:5], off offset:256
	global_load_dword v110, v[4:5], off offset:512
	global_load_dword v111, v[4:5], off offset:768
	global_load_dword v112, v[4:5], off offset:1024
	global_load_dword v113, v[4:5], off offset:1280
	global_load_dword v114, v[4:5], off offset:1536
	global_load_dword v115, v[4:5], off offset:1792
	global_load_dwordx4 v[116:119], v69, s[20:21] offset:192
	global_load_dwordx4 v[120:123], v69, s[20:21] offset:208
	global_load_dwordx4 v[124:127], v69, s[20:21] offset:224
	global_load_dwordx4 v[128:131], v69, s[20:21] offset:240
	v_lshl_add_u64 v[4:5], v[4:5], 0, s[4:5]
	s_waitcnt vmcnt(40)
; __device__ __forceinline__ void phase_prologue(Frame& F) {
;     ...
; #pragma unroll 16
;         for (int i = 0; i < 256; ++i) s += pe[i] * wp[(size_t)i * 64 + lane];
	v_fmac_f32_e32 v6, v148, v132
	v_fmac_f32_e32 v6, v149, v133
	v_fmac_f32_e32 v6, v150, v134
	v_fmac_f32_e32 v6, v151, v135
	v_fmac_f32_e32 v6, v152, v136
	v_fmac_f32_e32 v6, v153, v137
	v_fmac_f32_e32 v6, v154, v138
	v_fmac_f32_e32 v6, v155, v139
	v_fmac_f32_e32 v6, v156, v140
	v_fmac_f32_e32 v6, v157, v141
	v_fmac_f32_e32 v6, v158, v142
	v_fmac_f32_e32 v6, v159, v143
	v_fmac_f32_e32 v6, v160, v144
	v_fmac_f32_e32 v6, v161, v145
	v_fmac_f32_e32 v6, v162, v146
	v_fmac_f32_e32 v6, v163, v147
	global_load_dword v132, v[4:5], off offset:-2048
	global_load_dword v133, v[4:5], off offset:-1792
	global_load_dword v134, v[4:5], off offset:-1536
	global_load_dword v135, v[4:5], off offset:-1280
	global_load_dword v136, v[4:5], off offset:-1024
	global_load_dword v137, v[4:5], off offset:-768
	global_load_dword v138, v[4:5], off offset:-512
	global_load_dword v139, v[4:5], off offset:-256
	global_load_dword v140, v[4:5], off
	global_load_dword v141, v[4:5], off offset:256
	global_load_dword v142, v[4:5], off offset:512
	global_load_dword v143, v[4:5], off offset:768
	global_load_dword v144, v[4:5], off offset:1024
	global_load_dword v145, v[4:5], off offset:1280
	global_load_dword v146, v[4:5], off offset:1536
	global_load_dword v147, v[4:5], off offset:1792
	global_load_dwordx4 v[148:151], v69, s[20:21] offset:256
	global_load_dwordx4 v[152:155], v69, s[20:21] offset:272
	global_load_dwordx4 v[156:159], v69, s[20:21] offset:288
	global_load_dwordx4 v[160:163], v69, s[20:21] offset:304
	v_lshl_add_u64 v[4:5], v[4:5], 0, s[4:5]
	s_waitcnt vmcnt(40)
	v_fmac_f32_e32 v6, v180, v164
	v_fmac_f32_e32 v6, v181, v165
	v_fmac_f32_e32 v6, v182, v166
	v_fmac_f32_e32 v6, v183, v167
	v_fmac_f32_e32 v6, v184, v168
	v_fmac_f32_e32 v6, v185, v169
	v_fmac_f32_e32 v6, v186, v170
	v_fmac_f32_e32 v6, v187, v171
	v_fmac_f32_e32 v6, v188, v172
	v_fmac_f32_e32 v6, v189, v173
	v_fmac_f32_e32 v6, v190, v174
	v_fmac_f32_e32 v6, v191, v175
	v_fmac_f32_e32 v6, v192, v176
	v_fmac_f32_e32 v6, v193, v177
	v_fmac_f32_e32 v6, v194, v178
	v_fmac_f32_e32 v6, v195, v179
	global_load_dword v164, v[4:5], off offset:-2048
	global_load_dword v165, v[4:5], off offset:-1792
	global_load_dword v166, v[4:5], off offset:-1536
	global_load_dword v167, v[4:5], off offset:-1280
	global_load_dword v168, v[4:5], off offset:-1024
	global_load_dword v169, v[4:5], off offset:-768
	global_load_dword v170, v[4:5], off offset:-512
	global_load_dword v171, v[4:5], off offset:-256
	global_load_dword v172, v[4:5], off
	global_load_dword v173, v[4:5], off offset:256
	global_load_dword v174, v[4:5], off offset:512
	global_load_dword v175, v[4:5], off offset:768
	global_load_dword v176, v[4:5], off offset:1024
	global_load_dword v177, v[4:5], off offset:1280
	global_load_dword v178, v[4:5], off offset:1536
	global_load_dword v179, v[4:5], off offset:1792
	global_load_dwordx4 v[180:183], v69, s[20:21] offset:320
	global_load_dwordx4 v[184:187], v69, s[20:21] offset:336
	global_load_dwordx4 v[188:191], v69, s[20:21] offset:352
	global_load_dwordx4 v[192:195], v69, s[20:21] offset:368
	v_lshl_add_u64 v[4:5], v[4:5], 0, s[4:5]
	s_waitcnt vmcnt(40)
	v_fmac_f32_e32 v6, v116, v100
	v_fmac_f32_e32 v6, v117, v101
	v_fmac_f32_e32 v6, v118, v102
	v_fmac_f32_e32 v6, v119, v103
	v_fmac_f32_e32 v6, v120, v104
	v_fmac_f32_e32 v6, v121, v105
	v_fmac_f32_e32 v6, v122, v106
	v_fmac_f32_e32 v6, v123, v107
	v_fmac_f32_e32 v6, v124, v108
	v_fmac_f32_e32 v6, v125, v109
	v_fmac_f32_e32 v6, v126, v110
	v_fmac_f32_e32 v6, v127, v111
	v_fmac_f32_e32 v6, v128, v112
	v_fmac_f32_e32 v6, v129, v113
	v_fmac_f32_e32 v6, v130, v114
	v_fmac_f32_e32 v6, v131, v115
	global_load_dword v100, v[4:5], off offset:-2048
	global_load_dword v101, v[4:5], off offset:-1792
	global_load_dword v102, v[4:5], off offset:-1536
	global_load_dword v103, v[4:5], off offset:-1280
	global_load_dword v104, v[4:5], off offset:-1024
	global_load_dword v105, v[4:5], off offset:-768
	global_load_dword v106, v[4:5], off offset:-512
	global_load_dword v107, v[4:5], off offset:-256
	global_load_dword v108, v[4:5], off
	global_load_dword v109, v[4:5], off offset:256
	global_load_dword v110, v[4:5], off offset:512
	global_load_dword v111, v[4:5], off offset:768
	global_load_dword v112, v[4:5], off offset:1024
	global_load_dword v113, v[4:5], off offset:1280
	global_load_dword v114, v[4:5], off offset:1536
	global_load_dword v115, v[4:5], off offset:1792
	global_load_dwordx4 v[116:119], v69, s[20:21] offset:384
	global_load_dwordx4 v[120:123], v69, s[20:21] offset:400
	global_load_dwordx4 v[124:127], v69, s[20:21] offset:416
	global_load_dwordx4 v[128:131], v69, s[20:21] offset:432
	v_lshl_add_u64 v[4:5], v[4:5], 0, s[4:5]
	s_waitcnt vmcnt(40)
	v_fmac_f32_e32 v6, v148, v132
	v_fmac_f32_e32 v6, v149, v133
	v_fmac_f32_e32 v6, v150, v134
	v_fmac_f32_e32 v6, v151, v135
	v_fmac_f32_e32 v6, v152, v136
	v_fmac_f32_e32 v6, v153, v137
	v_fmac_f32_e32 v6, v154, v138
	v_fmac_f32_e32 v6, v155, v139
	v_fmac_f32_e32 v6, v156, v140
	v_fmac_f32_e32 v6, v157, v141
	v_fmac_f32_e32 v6, v158, v142
	v_fmac_f32_e32 v6, v159, v143
	v_fmac_f32_e32 v6, v160, v144
	v_fmac_f32_e32 v6, v161, v145
	v_fmac_f32_e32 v6, v162, v146
	v_fmac_f32_e32 v6, v163, v147
	global_load_dword v132, v[4:5], off offset:-2048
	global_load_dword v133, v[4:5], off offset:-1792
	global_load_dword v134, v[4:5], off offset:-1536
	global_load_dword v135, v[4:5], off offset:-1280
	global_load_dword v136, v[4:5], off offset:-1024
	global_load_dword v137, v[4:5], off offset:-768
	global_load_dword v138, v[4:5], off offset:-512
	global_load_dword v139, v[4:5], off offset:-256
	global_load_dword v140, v[4:5], off
	global_load_dword v141, v[4:5], off offset:256
	global_load_dword v142, v[4:5], off offset:512
	global_load_dword v143, v[4:5], off offset:768
	global_load_dword v144, v[4:5], off offset:1024
	global_load_dword v145, v[4:5], off offset:1280
	global_load_dword v146, v[4:5], off offset:1536
	global_load_dword v147, v[4:5], off offset:1792
	global_load_dwordx4 v[148:151], v69, s[20:21] offset:448
	global_load_dwordx4 v[152:155], v69, s[20:21] offset:464
	global_load_dwordx4 v[156:159], v69, s[20:21] offset:480
	global_load_dwordx4 v[160:163], v69, s[20:21] offset:496
	v_lshl_add_u64 v[4:5], v[4:5], 0, s[4:5]
	s_waitcnt vmcnt(40)
; __device__ __forceinline__ void phase_prologue(Frame& F) {
;     ...
; #pragma unroll 16
;         for (int i = 0; i < 256; ++i) s += pe[i] * wp[(size_t)i * 64 + lane];
	v_fmac_f32_e32 v6, v180, v164
	v_fmac_f32_e32 v6, v181, v165
	v_fmac_f32_e32 v6, v182, v166
	v_fmac_f32_e32 v6, v183, v167
	v_fmac_f32_e32 v6, v184, v168
	v_fmac_f32_e32 v6, v185, v169
	v_fmac_f32_e32 v6, v186, v170
	v_fmac_f32_e32 v6, v187, v171
	v_fmac_f32_e32 v6, v188, v172
	v_fmac_f32_e32 v6, v189, v173
	v_fmac_f32_e32 v6, v190, v174
	v_fmac_f32_e32 v6, v191, v175
	v_fmac_f32_e32 v6, v192, v176
	v_fmac_f32_e32 v6, v193, v177
	v_fmac_f32_e32 v6, v194, v178
	v_fmac_f32_e32 v6, v195, v179
	global_load_dword v164, v[4:5], off offset:-2048
	global_load_dword v165, v[4:5], off offset:-1792
	global_load_dword v166, v[4:5], off offset:-1536
	global_load_dword v167, v[4:5], off offset:-1280
	global_load_dword v168, v[4:5], off offset:-1024
	global_load_dword v169, v[4:5], off offset:-768
	global_load_dword v170, v[4:5], off offset:-512
	global_load_dword v171, v[4:5], off offset:-256
	global_load_dword v172, v[4:5], off
	global_load_dword v173, v[4:5], off offset:256
	global_load_dword v174, v[4:5], off offset:512
	global_load_dword v175, v[4:5], off offset:768
	global_load_dword v176, v[4:5], off offset:1024
	global_load_dword v177, v[4:5], off offset:1280
	global_load_dword v178, v[4:5], off offset:1536
	global_load_dword v179, v[4:5], off offset:1792
	global_load_dwordx4 v[180:183], v69, s[20:21] offset:512
	global_load_dwordx4 v[184:187], v69, s[20:21] offset:528
	global_load_dwordx4 v[188:191], v69, s[20:21] offset:544
	global_load_dwordx4 v[192:195], v69, s[20:21] offset:560
	v_lshl_add_u64 v[4:5], v[4:5], 0, s[4:5]
	s_waitcnt vmcnt(40)
	v_fmac_f32_e32 v6, v116, v100
	v_fmac_f32_e32 v6, v117, v101
	v_fmac_f32_e32 v6, v118, v102
	v_fmac_f32_e32 v6, v119, v103
	v_fmac_f32_e32 v6, v120, v104
	v_fmac_f32_e32 v6, v121, v105
	v_fmac_f32_e32 v6, v122, v106
	v_fmac_f32_e32 v6, v123, v107
	v_fmac_f32_e32 v6, v124, v108
	v_fmac_f32_e32 v6, v125, v109
	v_fmac_f32_e32 v6, v126, v110
	v_fmac_f32_e32 v6, v127, v111
	v_fmac_f32_e32 v6, v128, v112
	v_fmac_f32_e32 v6, v129, v113
	v_fmac_f32_e32 v6, v130, v114
	v_fmac_f32_e32 v6, v131, v115
	global_load_dword v100, v[4:5], off offset:-2048
	global_load_dword v101, v[4:5], off offset:-1792
	global_load_dword v102, v[4:5], off offset:-1536
	global_load_dword v103, v[4:5], off offset:-1280
	global_load_dword v104, v[4:5], off offset:-1024
	global_load_dword v105, v[4:5], off offset:-768
	global_load_dword v106, v[4:5], off offset:-512
	global_load_dword v107, v[4:5], off offset:-256
	global_load_dword v108, v[4:5], off
	global_load_dword v109, v[4:5], off offset:256
	global_load_dword v110, v[4:5], off offset:512
	global_load_dword v111, v[4:5], off offset:768
	global_load_dword v112, v[4:5], off offset:1024
	global_load_dword v113, v[4:5], off offset:1280
	global_load_dword v114, v[4:5], off offset:1536
	global_load_dword v115, v[4:5], off offset:1792
	global_load_dwordx4 v[116:119], v69, s[20:21] offset:576
	global_load_dwordx4 v[120:123], v69, s[20:21] offset:592
	global_load_dwordx4 v[124:127], v69, s[20:21] offset:608
	global_load_dwordx4 v[128:131], v69, s[20:21] offset:624
	v_lshl_add_u64 v[4:5], v[4:5], 0, s[4:5]
	s_waitcnt vmcnt(40)
	v_fmac_f32_e32 v6, v148, v132
	v_fmac_f32_e32 v6, v149, v133
	v_fmac_f32_e32 v6, v150, v134
	v_fmac_f32_e32 v6, v151, v135
	v_fmac_f32_e32 v6, v152, v136
	v_fmac_f32_e32 v6, v153, v137
	v_fmac_f32_e32 v6, v154, v138
	v_fmac_f32_e32 v6, v155, v139
	v_fmac_f32_e32 v6, v156, v140
	v_fmac_f32_e32 v6, v157, v141
	v_fmac_f32_e32 v6, v158, v142
	v_fmac_f32_e32 v6, v159, v143
	v_fmac_f32_e32 v6, v160, v144
	v_fmac_f32_e32 v6, v161, v145
	v_fmac_f32_e32 v6, v162, v146
	v_fmac_f32_e32 v6, v163, v147
	global_load_dword v132, v[4:5], off offset:-2048
	global_load_dword v133, v[4:5], off offset:-1792
	global_load_dword v134, v[4:5], off offset:-1536
	global_load_dword v135, v[4:5], off offset:-1280
	global_load_dword v136, v[4:5], off offset:-1024
	global_load_dword v137, v[4:5], off offset:-768
	global_load_dword v138, v[4:5], off offset:-512
	global_load_dword v139, v[4:5], off offset:-256
	global_load_dword v140, v[4:5], off
	global_load_dword v141, v[4:5], off offset:256
	global_load_dword v142, v[4:5], off offset:512
	global_load_dword v143, v[4:5], off offset:768
	global_load_dword v144, v[4:5], off offset:1024
	global_load_dword v145, v[4:5], off offset:1280
	global_load_dword v146, v[4:5], off offset:1536
	global_load_dword v147, v[4:5], off offset:1792
	global_load_dwordx4 v[148:151], v69, s[20:21] offset:640
	global_load_dwordx4 v[152:155], v69, s[20:21] offset:656
	global_load_dwordx4 v[156:159], v69, s[20:21] offset:672
	global_load_dwordx4 v[160:163], v69, s[20:21] offset:688
	v_lshl_add_u64 v[4:5], v[4:5], 0, s[4:5]
	s_waitcnt vmcnt(40)
	v_fmac_f32_e32 v6, v180, v164
	v_fmac_f32_e32 v6, v181, v165
	v_fmac_f32_e32 v6, v182, v166
	v_fmac_f32_e32 v6, v183, v167
	v_fmac_f32_e32 v6, v184, v168
	v_fmac_f32_e32 v6, v185, v169
	v_fmac_f32_e32 v6, v186, v170
	v_fmac_f32_e32 v6, v187, v171
	v_fmac_f32_e32 v6, v188, v172
	v_fmac_f32_e32 v6, v189, v173
	v_fmac_f32_e32 v6, v190, v174
	v_fmac_f32_e32 v6, v191, v175
	v_fmac_f32_e32 v6, v192, v176
	v_fmac_f32_e32 v6, v193, v177
	v_fmac_f32_e32 v6, v194, v178
	v_fmac_f32_e32 v6, v195, v179
	global_load_dword v164, v[4:5], off offset:-2048
	global_load_dword v165, v[4:5], off offset:-1792
	global_load_dword v166, v[4:5], off offset:-1536
	global_load_dword v167, v[4:5], off offset:-1280
	global_load_dword v168, v[4:5], off offset:-1024
	global_load_dword v169, v[4:5], off offset:-768
	global_load_dword v170, v[4:5], off offset:-512
	global_load_dword v171, v[4:5], off offset:-256
	global_load_dword v172, v[4:5], off
	global_load_dword v173, v[4:5], off offset:256
	global_load_dword v174, v[4:5], off offset:512
	global_load_dword v175, v[4:5], off offset:768
	global_load_dword v176, v[4:5], off offset:1024
	global_load_dword v177, v[4:5], off offset:1280
	global_load_dword v178, v[4:5], off offset:1536
	global_load_dword v179, v[4:5], off offset:1792
	global_load_dwordx4 v[180:183], v69, s[20:21] offset:704
	global_load_dwordx4 v[184:187], v69, s[20:21] offset:720
	global_load_dwordx4 v[188:191], v69, s[20:21] offset:736
	global_load_dwordx4 v[192:195], v69, s[20:21] offset:752
	v_lshl_add_u64 v[4:5], v[4:5], 0, s[4:5]
	s_waitcnt vmcnt(40)
; __device__ __forceinline__ void phase_prologue(Frame& F) {
;     ...
; #pragma unroll 16
;         for (int i = 0; i < 256; ++i) s += pe[i] * wp[(size_t)i * 64 + lane];
	v_fmac_f32_e32 v6, v116, v100
	v_fmac_f32_e32 v6, v117, v101
	v_fmac_f32_e32 v6, v118, v102
	v_fmac_f32_e32 v6, v119, v103
	v_fmac_f32_e32 v6, v120, v104
	v_fmac_f32_e32 v6, v121, v105
	v_fmac_f32_e32 v6, v122, v106
	v_fmac_f32_e32 v6, v123, v107
	v_fmac_f32_e32 v6, v124, v108
	v_fmac_f32_e32 v6, v125, v109
	v_fmac_f32_e32 v6, v126, v110
	v_fmac_f32_e32 v6, v127, v111
	v_fmac_f32_e32 v6, v128, v112
	v_fmac_f32_e32 v6, v129, v113
	v_fmac_f32_e32 v6, v130, v114
	v_fmac_f32_e32 v6, v131, v115
	global_load_dword v100, v[4:5], off offset:-2048
	global_load_dword v101, v[4:5], off offset:-1792
	global_load_dword v102, v[4:5], off offset:-1536
	global_load_dword v103, v[4:5], off offset:-1280
	global_load_dword v104, v[4:5], off offset:-1024
	global_load_dword v105, v[4:5], off offset:-768
	global_load_dword v106, v[4:5], off offset:-512
	global_load_dword v107, v[4:5], off offset:-256
	global_load_dword v108, v[4:5], off
	global_load_dword v109, v[4:5], off offset:256
	global_load_dword v110, v[4:5], off offset:512
	global_load_dword v111, v[4:5], off offset:768
	global_load_dword v112, v[4:5], off offset:1024
	global_load_dword v113, v[4:5], off offset:1280
	global_load_dword v114, v[4:5], off offset:1536
	global_load_dword v115, v[4:5], off offset:1792
	global_load_dwordx4 v[116:119], v69, s[20:21] offset:768
	global_load_dwordx4 v[120:123], v69, s[20:21] offset:784
	global_load_dwordx4 v[124:127], v69, s[20:21] offset:800
	global_load_dwordx4 v[128:131], v69, s[20:21] offset:816
	v_lshl_add_u64 v[4:5], v[4:5], 0, s[4:5]
	s_waitcnt vmcnt(40)
	v_fmac_f32_e32 v6, v148, v132
	v_fmac_f32_e32 v6, v149, v133
	v_fmac_f32_e32 v6, v150, v134
	v_fmac_f32_e32 v6, v151, v135
	v_fmac_f32_e32 v6, v152, v136
	v_fmac_f32_e32 v6, v153, v137
	v_fmac_f32_e32 v6, v154, v138
	v_fmac_f32_e32 v6, v155, v139
	v_fmac_f32_e32 v6, v156, v140
	v_fmac_f32_e32 v6, v157, v141
	v_fmac_f32_e32 v6, v158, v142
	v_fmac_f32_e32 v6, v159, v143
	v_fmac_f32_e32 v6, v160, v144
	v_fmac_f32_e32 v6, v161, v145
	v_fmac_f32_e32 v6, v162, v146
	v_fmac_f32_e32 v6, v163, v147
	global_load_dword v132, v[4:5], off offset:-2048
	global_load_dword v133, v[4:5], off offset:-1792
	global_load_dword v134, v[4:5], off offset:-1536
	global_load_dword v135, v[4:5], off offset:-1280
	global_load_dword v136, v[4:5], off offset:-1024
	global_load_dword v137, v[4:5], off offset:-768
	global_load_dword v138, v[4:5], off offset:-512
	global_load_dword v139, v[4:5], off offset:-256
	global_load_dword v140, v[4:5], off
	global_load_dword v141, v[4:5], off offset:256
	global_load_dword v142, v[4:5], off offset:512
	global_load_dword v143, v[4:5], off offset:768
	global_load_dword v144, v[4:5], off offset:1024
	global_load_dword v145, v[4:5], off offset:1280
	global_load_dword v146, v[4:5], off offset:1536
	global_load_dword v147, v[4:5], off offset:1792
	global_load_dwordx4 v[148:151], v69, s[20:21] offset:832
	global_load_dwordx4 v[152:155], v69, s[20:21] offset:848
	global_load_dwordx4 v[156:159], v69, s[20:21] offset:864
	global_load_dwordx4 v[160:163], v69, s[20:21] offset:880
	v_lshl_add_u64 v[4:5], v[4:5], 0, s[4:5]
	s_waitcnt vmcnt(40)
	v_fmac_f32_e32 v6, v180, v164
	v_fmac_f32_e32 v6, v181, v165
	v_fmac_f32_e32 v6, v182, v166
	v_fmac_f32_e32 v6, v183, v167
	v_fmac_f32_e32 v6, v184, v168
	v_fmac_f32_e32 v6, v185, v169
	v_fmac_f32_e32 v6, v186, v170
	v_fmac_f32_e32 v6, v187, v171
	v_fmac_f32_e32 v6, v188, v172
	v_fmac_f32_e32 v6, v189, v173
	v_fmac_f32_e32 v6, v190, v174
	v_fmac_f32_e32 v6, v191, v175
	v_fmac_f32_e32 v6, v192, v176
	v_fmac_f32_e32 v6, v193, v177
	v_fmac_f32_e32 v6, v194, v178
	v_fmac_f32_e32 v6, v195, v179
	global_load_dword v164, v[4:5], off offset:-2048
	global_load_dword v165, v[4:5], off offset:-1792
	global_load_dword v166, v[4:5], off offset:-1536
	global_load_dword v167, v[4:5], off offset:-1280
	global_load_dword v168, v[4:5], off offset:-1024
	global_load_dword v169, v[4:5], off offset:-768
	global_load_dword v170, v[4:5], off offset:-512
	global_load_dword v171, v[4:5], off offset:-256
	global_load_dword v172, v[4:5], off
	global_load_dword v173, v[4:5], off offset:256
	global_load_dword v174, v[4:5], off offset:512
	global_load_dword v175, v[4:5], off offset:768
	global_load_dword v176, v[4:5], off offset:1024
	global_load_dword v177, v[4:5], off offset:1280
	global_load_dword v178, v[4:5], off offset:1536
	global_load_dword v179, v[4:5], off offset:1792
	global_load_dwordx4 v[180:183], v69, s[20:21] offset:896
	global_load_dwordx4 v[184:187], v69, s[20:21] offset:912
	global_load_dwordx4 v[188:191], v69, s[20:21] offset:928
	global_load_dwordx4 v[192:195], v69, s[20:21] offset:944
	v_lshl_add_u64 v[4:5], v[4:5], 0, s[4:5]
	s_waitcnt vmcnt(40)
; __device__ __forceinline__ void phase_prologue(Frame& F) {
;     ...
; #pragma unroll 16
;         for (int i = 0; i < 256; ++i) s += pe[i] * wp[(size_t)i * 64 + lane];
;         ((float*)(F.ws + WS_PEBP + l * al1m(SZ_PEBP)))[(j * 16 + part) * 64 + lane] = s;
;     }
	v_fmac_f32_e32 v6, v116, v100
	v_fmac_f32_e32 v6, v117, v101
	v_fmac_f32_e32 v6, v118, v102
	v_fmac_f32_e32 v6, v119, v103
	v_fmac_f32_e32 v6, v120, v104
	v_fmac_f32_e32 v6, v121, v105
	v_fmac_f32_e32 v6, v122, v106
	v_fmac_f32_e32 v6, v123, v107
	v_fmac_f32_e32 v6, v124, v108
	v_fmac_f32_e32 v6, v125, v109
	v_fmac_f32_e32 v6, v126, v110
	v_fmac_f32_e32 v6, v127, v111
	v_fmac_f32_e32 v6, v128, v112
	v_fmac_f32_e32 v6, v129, v113
	v_fmac_f32_e32 v6, v130, v114
	v_fmac_f32_e32 v6, v131, v115
	global_load_dword v100, v[4:5], off offset:-2048
	global_load_dword v101, v[4:5], off offset:-1792
	global_load_dword v102, v[4:5], off offset:-1536
	global_load_dword v103, v[4:5], off offset:-1280
	global_load_dword v104, v[4:5], off offset:-1024
	global_load_dword v105, v[4:5], off offset:-768
	global_load_dword v106, v[4:5], off offset:-512
	global_load_dword v107, v[4:5], off offset:-256
	global_load_dword v108, v[4:5], off
	global_load_dword v109, v[4:5], off offset:256
	global_load_dword v110, v[4:5], off offset:512
	global_load_dword v111, v[4:5], off offset:768
	global_load_dword v112, v[4:5], off offset:1024
	global_load_dword v113, v[4:5], off offset:1280
	global_load_dword v114, v[4:5], off offset:1536
	global_load_dword v115, v[4:5], off offset:1792
	global_load_dwordx4 v[116:119], v69, s[20:21] offset:960
	global_load_dwordx4 v[120:123], v69, s[20:21] offset:976
	global_load_dwordx4 v[124:127], v69, s[20:21] offset:992
	global_load_dwordx4 v[128:131], v69, s[20:21] offset:1008
	v_lshl_add_u64 v[4:5], v[4:5], 0, s[4:5]
	s_waitcnt vmcnt(40)
	v_fmac_f32_e32 v6, v148, v132
	v_fmac_f32_e32 v6, v149, v133
	v_fmac_f32_e32 v6, v150, v134
	v_fmac_f32_e32 v6, v151, v135
	v_fmac_f32_e32 v6, v152, v136
	v_fmac_f32_e32 v6, v153, v137
	v_fmac_f32_e32 v6, v154, v138
	v_fmac_f32_e32 v6, v155, v139
	v_fmac_f32_e32 v6, v156, v140
	v_fmac_f32_e32 v6, v157, v141
	v_fmac_f32_e32 v6, v158, v142
	v_fmac_f32_e32 v6, v159, v143
	v_fmac_f32_e32 v6, v160, v144
	v_fmac_f32_e32 v6, v161, v145
	v_fmac_f32_e32 v6, v162, v146
	v_fmac_f32_e32 v6, v163, v147
	s_waitcnt vmcnt(20)
	v_fmac_f32_e32 v6, v180, v164
	v_fmac_f32_e32 v6, v181, v165
	v_fmac_f32_e32 v6, v182, v166
	v_fmac_f32_e32 v6, v183, v167
	v_fmac_f32_e32 v6, v184, v168
	v_fmac_f32_e32 v6, v185, v169
	v_fmac_f32_e32 v6, v186, v170
	v_fmac_f32_e32 v6, v187, v171
	v_fmac_f32_e32 v6, v188, v172
	v_fmac_f32_e32 v6, v189, v173
	v_fmac_f32_e32 v6, v190, v174
	v_fmac_f32_e32 v6, v191, v175
	v_fmac_f32_e32 v6, v192, v176
	v_fmac_f32_e32 v6, v193, v177
	v_fmac_f32_e32 v6, v194, v178
	v_fmac_f32_e32 v6, v195, v179
	s_waitcnt vmcnt(0)
	v_fmac_f32_e32 v6, v116, v100
	v_fmac_f32_e32 v6, v117, v101
	v_fmac_f32_e32 v6, v118, v102
	v_fmac_f32_e32 v6, v119, v103
	v_fmac_f32_e32 v6, v120, v104
	v_fmac_f32_e32 v6, v121, v105
	v_fmac_f32_e32 v6, v122, v106
	v_fmac_f32_e32 v6, v123, v107
	v_fmac_f32_e32 v6, v124, v108
	v_fmac_f32_e32 v6, v125, v109
	v_fmac_f32_e32 v6, v126, v110
	v_fmac_f32_e32 v6, v127, v111
	v_fmac_f32_e32 v6, v128, v112
	v_fmac_f32_e32 v6, v129, v113
	v_fmac_f32_e32 v6, v130, v114
	v_fmac_f32_e32 v6, v131, v115
	s_ashr_i32 s7, s6, 31
	s_lshl_b64 s[6:7], s[6:7], 20
	s_add_u32 s6, s12, s6
	s_addc_u32 s7, s13, s7
	s_lshl_b32 s10, s17, 6
	s_and_b32 s10, s10, 0x7c0
	v_or_b32_e32 v4, s10, v1
	s_add_i32 s17, s17, s88
	s_add_i32 s15, s15, s16
	v_lshlrev_b32_e32 v4, 2, v4
	s_cmp_gt_i32 s17, 63
	global_store_dword v4, v6, s[6:7]
	s_cbranch_scc0 .LBB0_71

; #define FIN(i) ((const float*)(const GAS float*)(((const float* const __attribute__((address_space(4)))*)__builtin_amdgcn_kernarg_segment_ptr())[i]))
; __device__ __forceinline__ double exp_d(double x) {
;     const double r = x * (1.0 / 64.0); double t = 1.0, s = 1.0;
; #pragma unroll
;     for (int k = 1; k <= 14; ++k) { t *= r / (double)k; s += t; }
; #pragma unroll
;     for (int k = 0; k < 6; ++k) s *= s;
;     return s;
; }
; __device__ __forceinline__ void phase_prologue(Frame& F) {
;     ...
;         const double dt = exp_d((double)FIN(IN_LSTEP)[l * 64 + g]);
;         const double lr = (double)FIN(IN_LRE)[(l * 64 + g) * 64 + n], li = (double)FIN(IN_LIM)[(l * 64 + g) * 64 + n];
;         const double mag = exp_d(lr * dt); double sn, cs; sincos_d(li * dt, sn, cs);
.LBB0_77:
	s_or_b64 exec, exec, s[6:7]
	s_waitcnt vmcnt(0)
	v_cvt_f64_f32_e32 v[22:23], v4
	v_mul_f64 v[20:21], v[20:21], v[22:23]
	v_ldexp_f64 v[24:25], v[20:21], -6
	v_div_scale_f64 v[28:29], s[6:7], s[44:45], s[44:45], v[24:25]
	v_rcp_f64_e32 v[32:33], v[28:29]
	v_fma_f64 v[20:21], v[20:21], s[42:43], 1.0
	v_mul_f64 v[34:35], v[24:25], 0.5
	v_mul_f64 v[36:37], v[24:25], v[34:35]
	v_fmac_f64_e32 v[20:21], v[24:25], v[34:35]
	v_fma_f64 v[34:35], -v[28:29], v[32:33], 1.0
	v_fmac_f64_e32 v[32:33], v[32:33], v[34:35]
	v_fma_f64 v[34:35], -v[28:29], v[32:33], 1.0
	v_fmac_f64_e32 v[32:33], v[32:33], v[34:35]
	v_div_scale_f64 v[34:35], vcc, v[24:25], s[44:45], v[24:25]
	v_mul_f64 v[38:39], v[34:35], v[32:33]
	v_fma_f64 v[28:29], -v[28:29], v[38:39], v[34:35]
	v_ashrrev_i32_e32 v15, 31, v14
	s_nop 0
	v_div_fmas_f64 v[28:29], v[28:29], v[32:33], v[38:39]
	v_div_fixup_f64 v[28:29], v[28:29], s[44:45], v[24:25]
	v_mul_f64 v[32:33], v[28:29], v[36:37]
	v_fmac_f64_e32 v[20:21], v[28:29], v[36:37]
	v_div_scale_f64 v[28:29], s[6:7], s[46:47], s[46:47], v[24:25]
	v_rcp_f64_e32 v[34:35], v[28:29]
	v_ldexp_f64 v[36:37], v[24:25], -2
	v_mul_f64 v[38:39], v[36:37], v[32:33]
	v_fmac_f64_e32 v[20:21], v[36:37], v[32:33]
	v_fma_f64 v[32:33], -v[28:29], v[34:35], 1.0
	v_fmac_f64_e32 v[34:35], v[34:35], v[32:33]
	v_fma_f64 v[32:33], -v[28:29], v[34:35], 1.0
	v_fmac_f64_e32 v[34:35], v[34:35], v[32:33]
	v_div_scale_f64 v[32:33], vcc, v[24:25], s[46:47], v[24:25]
	v_mul_f64 v[36:37], v[32:33], v[34:35]
	v_fma_f64 v[28:29], -v[28:29], v[36:37], v[32:33]
	v_div_scale_f64 v[32:33], s[6:7], s[48:49], s[48:49], v[24:25]
	s_nop 0
	v_div_fmas_f64 v[28:29], v[28:29], v[34:35], v[36:37]
	v_rcp_f64_e32 v[34:35], v[32:33]
	v_div_fixup_f64 v[28:29], v[28:29], s[46:47], v[24:25]
	v_mul_f64 v[36:37], v[28:29], v[38:39]
	v_fmac_f64_e32 v[20:21], v[28:29], v[38:39]
	v_fma_f64 v[28:29], -v[32:33], v[34:35], 1.0
	v_fmac_f64_e32 v[34:35], v[34:35], v[28:29]
	v_fma_f64 v[28:29], -v[32:33], v[34:35], 1.0
	v_fmac_f64_e32 v[34:35], v[34:35], v[28:29]
	v_div_scale_f64 v[28:29], vcc, v[24:25], s[48:49], v[24:25]
	v_mul_f64 v[38:39], v[28:29], v[34:35]
	v_fma_f64 v[28:29], -v[32:33], v[38:39], v[28:29]
	v_div_scale_f64 v[32:33], s[6:7], s[50:51], s[50:51], v[24:25]
	s_nop 0
	v_div_fmas_f64 v[28:29], v[28:29], v[34:35], v[38:39]
	v_rcp_f64_e32 v[34:35], v[32:33]
	v_div_fixup_f64 v[28:29], v[28:29], s[48:49], v[24:25]
	v_mul_f64 v[38:39], v[28:29], v[36:37]
	v_fmac_f64_e32 v[20:21], v[28:29], v[36:37]
	v_fma_f64 v[28:29], -v[32:33], v[34:35], 1.0
	v_fmac_f64_e32 v[34:35], v[34:35], v[28:29]
	v_fma_f64 v[28:29], -v[32:33], v[34:35], 1.0
	v_fmac_f64_e32 v[34:35], v[34:35], v[28:29]
	v_div_scale_f64 v[28:29], vcc, v[24:25], s[50:51], v[24:25]
	v_mul_f64 v[36:37], v[28:29], v[34:35]
	v_fma_f64 v[28:29], -v[32:33], v[36:37], v[28:29]
	s_load_dwordx4 s[8:11], s[0:1], 0x90
	s_nop 0
	v_div_fmas_f64 v[28:29], v[28:29], v[34:35], v[36:37]
	v_div_fixup_f64 v[28:29], v[28:29], s[50:51], v[24:25]
	v_mul_f64 v[32:33], v[28:29], v[38:39]
	v_fmac_f64_e32 v[20:21], v[28:29], v[38:39]
	v_div_scale_f64 v[28:29], s[6:7], s[52:53], s[52:53], v[24:25]
	v_rcp_f64_e32 v[34:35], v[28:29]
	v_ldexp_f64 v[36:37], v[24:25], -3
	v_mul_f64 v[38:39], v[36:37], v[32:33]
	v_fmac_f64_e32 v[20:21], v[36:37], v[32:33]
	v_fma_f64 v[32:33], -v[28:29], v[34:35], 1.0
	v_fmac_f64_e32 v[34:35], v[34:35], v[32:33]
	v_fma_f64 v[32:33], -v[28:29], v[34:35], 1.0
	v_fmac_f64_e32 v[34:35], v[34:35], v[32:33]
	v_div_scale_f64 v[32:33], vcc, v[24:25], s[52:53], v[24:25]
	v_mul_f64 v[36:37], v[32:33], v[34:35]
	v_fma_f64 v[28:29], -v[28:29], v[36:37], v[32:33]
	v_div_scale_f64 v[32:33], s[6:7], s[54:55], s[54:55], v[24:25]
	s_nop 0
	v_div_fmas_f64 v[28:29], v[28:29], v[34:35], v[36:37]
	v_rcp_f64_e32 v[34:35], v[32:33]
	v_div_fixup_f64 v[28:29], v[28:29], s[52:53], v[24:25]
	v_mul_f64 v[36:37], v[28:29], v[38:39]
	v_fmac_f64_e32 v[20:21], v[28:29], v[38:39]
	v_fma_f64 v[28:29], -v[32:33], v[34:35], 1.0
	v_fmac_f64_e32 v[34:35], v[34:35], v[28:29]
	v_fma_f64 v[28:29], -v[32:33], v[34:35], 1.0
	v_fmac_f64_e32 v[34:35], v[34:35], v[28:29]
	v_div_scale_f64 v[28:29], vcc, v[24:25], s[54:55], v[24:25]
	v_mul_f64 v[38:39], v[28:29], v[34:35]
	v_fma_f64 v[28:29], -v[32:33], v[38:39], v[28:29]
	v_div_scale_f64 v[32:33], s[6:7], s[56:57], s[56:57], v[24:25]
	s_nop 0
	v_div_fmas_f64 v[28:29], v[28:29], v[34:35], v[38:39]
	v_rcp_f64_e32 v[34:35], v[32:33]
	v_div_fixup_f64 v[28:29], v[28:29], s[54:55], v[24:25]
	v_mul_f64 v[38:39], v[28:29], v[36:37]
	v_fmac_f64_e32 v[20:21], v[28:29], v[36:37]
	v_fma_f64 v[28:29], -v[32:33], v[34:35], 1.0
	v_fmac_f64_e32 v[34:35], v[34:35], v[28:29]
	v_fma_f64 v[28:29], -v[32:33], v[34:35], 1.0
	v_fmac_f64_e32 v[34:35], v[34:35], v[28:29]
	v_div_scale_f64 v[28:29], vcc, v[24:25], s[56:57], v[24:25]
	v_mul_f64 v[36:37], v[28:29], v[34:35]
	v_fma_f64 v[28:29], -v[32:33], v[36:37], v[28:29]
	v_div_scale_f64 v[32:33], s[6:7], s[58:59], s[58:59], v[24:25]
	s_nop 0
	v_div_fmas_f64 v[28:29], v[28:29], v[34:35], v[36:37]
	v_rcp_f64_e32 v[34:35], v[32:33]
	v_div_fixup_f64 v[28:29], v[28:29], s[56:57], v[24:25]
	v_mul_f64 v[36:37], v[28:29], v[38:39]
	v_fmac_f64_e32 v[20:21], v[28:29], v[38:39]
	v_fma_f64 v[28:29], -v[32:33], v[34:35], 1.0
	v_fmac_f64_e32 v[34:35], v[34:35], v[28:29]
	v_fma_f64 v[28:29], -v[32:33], v[34:35], 1.0
	v_fmac_f64_e32 v[34:35], v[34:35], v[28:29]
	v_div_scale_f64 v[28:29], vcc, v[24:25], s[58:59], v[24:25]
	v_mul_f64 v[38:39], v[28:29], v[34:35]
	v_fma_f64 v[28:29], -v[32:33], v[38:39], v[28:29]
	v_div_scale_f64 v[32:33], s[6:7], s[60:61], s[60:61], v[24:25]
	s_nop 0
	v_div_fmas_f64 v[28:29], v[28:29], v[34:35], v[38:39]
; #define FIN(i) ((const float*)(const GAS float*)(((const float* const __attribute__((address_space(4)))*)__builtin_amdgcn_kernarg_segment_ptr())[i]))
; __device__ __forceinline__ void phase_prologue(Frame& F) {
;     ...
;         const double ar = mag * cs, ai = mag * sn, den = lr * lr + li * li;
;         const double cr = ((ar - 1.0) * lr + ai * li) / den, ci = (ai * lr - (ar - 1.0) * li) / den;
;         double pr = ar, pi = ai;
; #pragma unroll
;         for (int k = 0; k < 7; ++k) { const double t = pr * pr - pi * pi; pi = 2.0 * pr * pi; pr = t; }
;         float* ab = (float*)(F.ws + WS_SAB + l * al1m(SZ_SAB)) + (g * 64 + n) * 4;
;         ab[0] = (float)ar; ab[1] = (float)ai; ab[2] = (float)pr; ab[3] = (float)pi;
;         float* bb = (float*)(F.ws + WS_SBB + l * al1m(SZ_SBB)) + (size_t)g * 16 * 128;
;         const float* bre = FIN(IN_BRE) + ((size_t)(l * 64 + g) * 64 + n) * 16; const float* bim = FIN(IN_BIM) + ((size_t)(l * 64 + g) * 64 + n) * 16;
;         unsigned* bb16 = (unsigned*)(F.ws + WS_SBB16 + l * al1m(SZ_SBB16));
;         for (int c = 0; c < 16; c += 2) { const double br0 = bre[c], bi0 = bim[c], br1 = bre[c + 1], bi1 = bim[c + 1];
;             const float r0 = (float)(cr * br0 - ci * bi0), i0 = (float)(cr * bi0 + ci * br0), r1 = (float)(cr * br1 - ci * bi1), i1 = (float)(cr * bi1 + ci * br1);
	v_rcp_f64_e32 v[34:35], v[32:33]
	v_div_fixup_f64 v[28:29], v[28:29], s[58:59], v[24:25]
	v_mul_f64 v[38:39], v[28:29], v[36:37]
	v_fmac_f64_e32 v[20:21], v[28:29], v[36:37]
	v_fma_f64 v[28:29], -v[32:33], v[34:35], 1.0
	v_fmac_f64_e32 v[34:35], v[34:35], v[28:29]
	v_fma_f64 v[28:29], -v[32:33], v[34:35], 1.0
	v_fmac_f64_e32 v[34:35], v[34:35], v[28:29]
	v_div_scale_f64 v[28:29], vcc, v[24:25], s[60:61], v[24:25]
	v_mul_f64 v[36:37], v[28:29], v[34:35]
	v_fma_f64 v[28:29], -v[32:33], v[36:37], v[28:29]
	v_div_scale_f64 v[32:33], s[6:7], s[62:63], s[62:63], v[24:25]
	s_nop 0
	v_div_fmas_f64 v[28:29], v[28:29], v[34:35], v[36:37]
	v_rcp_f64_e32 v[34:35], v[32:33]
	v_div_fixup_f64 v[28:29], v[28:29], s[60:61], v[24:25]
	v_mul_f64 v[36:37], v[28:29], v[38:39]
	v_fmac_f64_e32 v[20:21], v[28:29], v[38:39]
	v_fma_f64 v[28:29], -v[32:33], v[34:35], 1.0
	v_fmac_f64_e32 v[34:35], v[34:35], v[28:29]
	v_fma_f64 v[28:29], -v[32:33], v[34:35], 1.0
	v_fmac_f64_e32 v[34:35], v[34:35], v[28:29]
	v_div_scale_f64 v[28:29], vcc, v[24:25], s[62:63], v[24:25]
	v_mul_f64 v[38:39], v[28:29], v[34:35]
	v_fma_f64 v[28:29], -v[32:33], v[38:39], v[28:29]
	v_lshlrev_b64 v[14:15], 20, v[14:15]
	s_nop 0
	v_div_fmas_f64 v[28:29], v[28:29], v[34:35], v[38:39]
	v_div_fixup_f64 v[24:25], v[28:29], s[62:63], v[24:25]
	v_fmac_f64_e32 v[20:21], v[24:25], v[36:37]
	v_mul_f64 v[20:21], v[20:21], v[20:21]
	v_mul_f64 v[20:21], v[20:21], v[20:21]
	v_mul_f64 v[20:21], v[20:21], v[20:21]
	v_mul_f64 v[20:21], v[20:21], v[20:21]
	v_mul_f64 v[20:21], v[20:21], v[20:21]
	v_mul_f64 v[28:29], v[20:21], v[20:21]
	v_mul_f64 v[20:21], v[28:29], v[18:19]
	v_mul_f64 v[32:33], v[28:29], v[26:27]
	v_add_f64 v[26:27], v[20:21], v[20:21]
	v_mul_f64 v[24:25], v[32:33], v[32:33]
	v_mul_f64 v[26:27], v[32:33], v[26:27]
	v_fma_f64 v[24:25], v[20:21], v[20:21], -v[24:25]
	v_mul_f64 v[34:35], v[26:27], v[26:27]
	v_fma_f64 v[34:35], v[24:25], v[24:25], -v[34:35]
	v_add_f64 v[24:25], v[24:25], v[24:25]
	v_mul_f64 v[24:25], v[26:27], v[24:25]
	v_mul_f64 v[26:27], v[24:25], v[24:25]
	v_fma_f64 v[26:27], v[34:35], v[34:35], -v[26:27]
	v_add_f64 v[34:35], v[34:35], v[34:35]
	v_mul_f64 v[24:25], v[24:25], v[34:35]
	v_mul_f64 v[34:35], v[24:25], v[24:25]
	v_fma_f64 v[34:35], v[26:27], v[26:27], -v[34:35]
	v_add_f64 v[26:27], v[26:27], v[26:27]
	v_mul_f64 v[24:25], v[24:25], v[26:27]
	v_mul_f64 v[26:27], v[24:25], v[24:25]
	v_fma_f64 v[26:27], v[34:35], v[34:35], -v[26:27]
	v_add_f64 v[34:35], v[34:35], v[34:35]
	v_mul_f64 v[24:25], v[24:25], v[34:35]
	v_mul_f64 v[34:35], v[24:25], v[24:25]
	v_fma_f64 v[34:35], v[26:27], v[26:27], -v[34:35]
	v_add_f64 v[26:27], v[26:27], v[26:27]
	v_mul_f64 v[24:25], v[24:25], v[26:27]
	v_mul_f64 v[26:27], v[24:25], v[24:25]
	v_fma_f64 v[26:27], v[34:35], v[34:35], -v[26:27]
	v_add_f64 v[34:35], v[34:35], v[34:35]
	v_and_b32_e32 v4, 0x3ffc, v30
	v_mul_f64 v[34:35], v[24:25], v[34:35]
	v_lshl_add_u64 v[24:25], s[34:35], 0, v[14:15]
	v_lshlrev_b32_e32 v4, 2, v4
	v_lshl_add_u64 v[36:37], v[24:25], 0, v[4:5]
	v_cvt_f32_f64_e32 v24, v[20:21]
	v_cvt_f32_f64_e32 v26, v[26:27]
	v_cvt_f32_f64_e32 v25, v[32:33]
	v_cvt_f32_f64_e32 v27, v[34:35]
	v_lshlrev_b64 v[12:13], 12, v[12:13]
	global_store_dwordx4 v[36:37], v[24:27], off
	v_fma_f64 v[18:19], v[28:29], v[18:19], -1.0
	v_mul_f64 v[36:37], v[16:17], v[16:17]
	v_lshl_or_b32 v24, v2, 2, v12
	v_mov_b32_e32 v25, v13
	v_lshl_add_u64 v[20:21], s[22:23], 0, v[24:25]
	s_waitcnt lgkmcnt(0)
	v_lshl_add_u64 v[24:25], s[8:9], 0, v[24:25]
	global_load_dwordx2 v[34:35], v[24:25], off
	global_load_dwordx2 v[26:27], v[20:21], off
	global_load_dwordx2 v[100:101], v[20:21], off offset:8
	global_load_dwordx2 v[102:103], v[24:25], off offset:8
	global_load_dwordx2 v[104:105], v[20:21], off offset:16
	global_load_dwordx2 v[106:107], v[24:25], off offset:16
	global_load_dwordx2 v[108:109], v[20:21], off offset:24
	global_load_dwordx2 v[110:111], v[24:25], off offset:24
	global_load_dwordx2 v[112:113], v[20:21], off offset:32
	global_load_dwordx2 v[114:115], v[24:25], off offset:32
	global_load_dwordx2 v[116:117], v[20:21], off offset:40
	global_load_dwordx2 v[118:119], v[24:25], off offset:40
	global_load_dwordx2 v[120:121], v[20:21], off offset:48
	global_load_dwordx2 v[122:123], v[24:25], off offset:48
	global_load_dwordx2 v[124:125], v[20:21], off offset:56
	global_load_dwordx2 v[126:127], v[24:25], off offset:56
	v_mul_f64 v[28:29], v[18:19], v[22:23]
	v_fmac_f64_e32 v[28:29], v[32:33], v[16:17]
	v_fmac_f64_e32 v[36:37], v[22:23], v[22:23]
	v_div_scale_f64 v[38:39], s[6:7], v[36:37], v[36:37], v[28:29]
	v_rcp_f64_e32 v[40:41], v[38:39]
	v_mul_f64 v[16:17], v[18:19], v[16:17]
	v_fma_f64 v[18:19], v[32:33], v[22:23], -v[16:17]
	v_div_scale_f64 v[32:33], s[6:7], v[36:37], v[36:37], v[18:19]
	v_fma_f64 v[16:17], -v[38:39], v[40:41], 1.0
	v_fmac_f64_e32 v[40:41], v[40:41], v[16:17]
	v_fma_f64 v[16:17], -v[38:39], v[40:41], 1.0
	v_fmac_f64_e32 v[40:41], v[40:41], v[16:17]
	v_div_scale_f64 v[16:17], vcc, v[28:29], v[36:37], v[28:29]
	v_mul_f64 v[22:23], v[16:17], v[40:41]
	v_fma_f64 v[16:17], -v[38:39], v[22:23], v[16:17]
	v_rcp_f64_e32 v[38:39], v[32:33]
	s_nop 0
	v_div_fmas_f64 v[16:17], v[16:17], v[40:41], v[22:23]
	v_div_fixup_f64 v[16:17], v[16:17], v[36:37], v[28:29]
	v_lshlrev_b32_e32 v4, 13, v11
	v_fma_f64 v[22:23], -v[32:33], v[38:39], 1.0
	v_fmac_f64_e32 v[38:39], v[38:39], v[22:23]
	v_fma_f64 v[22:23], -v[32:33], v[38:39], 1.0
	v_fmac_f64_e32 v[38:39], v[38:39], v[22:23]
	v_div_scale_f64 v[22:23], vcc, v[18:19], v[36:37], v[18:19]
	v_mul_f64 v[28:29], v[22:23], v[38:39]
	v_fma_f64 v[22:23], -v[32:33], v[28:29], v[22:23]
	v_mov_b32_e32 v69, v5
	s_nop 0
	v_div_fmas_f64 v[22:23], v[22:23], v[38:39], v[28:29]
	v_div_fixup_f64 v[18:19], v[22:23], v[36:37], v[18:19]
	v_lshl_add_u64 v[22:23], s[36:37], 0, v[14:15]
	v_lshl_add_u64 v[22:23], v[22:23], 0, v[4:5]
	v_lshl_add_u64 v[22:23], v[22:23], 0, v[68:69]
	s_movk_i32 s6, 0x1000
	v_add_u32_e32 v3, s91, v3
	v_add_u32_e32 v30, s3, v30
	s_waitcnt vmcnt(15)
; __device__ __forceinline__ unsigned pk2(float lo, float hi) { f32x2 v = {lo, hi}; bf16x2_t b = __builtin_convertvector(v, bf16x2_t); return __builtin_bit_cast(unsigned, b); }
; __device__ __forceinline__ void phase_prologue(Frame& F) {
;     ...
;         for (int c = 0; c < 16; c += 2) { const double br0 = bre[c], bi0 = bim[c], br1 = bre[c + 1], bi1 = bim[c + 1];
;             const float r0 = (float)(cr * br0 - ci * bi0), i0 = (float)(cr * bi0 + ci * br0), r1 = (float)(cr * br1 - ci * bi1), i1 = (float)(cr * bi1 + ci * br1);
;             bb[c * 128 + n] = r0; bb[c * 128 + 64 + n] = i0; bb[(c + 1) * 128 + n] = r1; bb[(c + 1) * 128 + 64 + n] = i1;
;             bb16[(((g * 2 + 0) * 64 + n) * 16 + c) >> 1] = pk2(r0, r1); bb16[(((g * 2 + 1) * 64 + n) * 16 + c) >> 1] = pk2(i0, i1); }
	v_cvt_f64_f32_e32 v[32:33], v35
	v_cvt_f64_f32_e32 v[34:35], v34
	s_waitcnt vmcnt(14)
	v_cvt_f64_f32_e32 v[28:29], v27
	v_cvt_f64_f32_e32 v[26:27], v26
	v_mul_f64 v[36:37], v[16:17], v[34:35]
	v_mul_f64 v[34:35], v[18:19], v[34:35]
	v_fmac_f64_e32 v[36:37], v[18:19], v[26:27]
	v_fma_f64 v[26:27], v[16:17], v[26:27], -v[34:35]
	v_cvt_f32_f64_e32 v31, v[36:37]
	v_mul_f64 v[36:37], v[18:19], v[32:33]
	v_cvt_f32_f64_e32 v41, v[26:27]
	v_mul_f64 v[26:27], v[16:17], v[32:33]
	v_fma_f64 v[34:35], v[16:17], v[28:29], -v[36:37]
	v_fmac_f64_e32 v[26:27], v[18:19], v[28:29]
	v_cvt_f32_f64_e32 v40, v[34:35]
	v_cvt_f32_f64_e32 v42, v[26:27]
	global_store_dword v[22:23], v41, off
	global_store_dword v[22:23], v31, off offset:256
	global_store_dword v[22:23], v40, off offset:512
	global_store_dword v[22:23], v42, off offset:768
	s_waitcnt vmcnt(4)
	v_mov_b32_e32 v26, v100
	v_mov_b32_e32 v27, v101
	v_mov_b32_e32 v28, v102
	v_mov_b32_e32 v29, v103
	v_cvt_f64_f32_e32 v[32:33], v27
	v_cvt_f64_f32_e32 v[34:35], v29
	v_cvt_f64_f32_e32 v[28:29], v28
	v_cvt_f64_f32_e32 v[26:27], v26
	v_mul_f64 v[36:37], v[16:17], v[28:29]
	v_mul_f64 v[28:29], v[18:19], v[28:29]
	v_fmac_f64_e32 v[36:37], v[18:19], v[26:27]
	v_fma_f64 v[26:27], v[16:17], v[26:27], -v[28:29]
	v_cvt_f32_f64_e32 v43, v[36:37]
	v_mul_f64 v[36:37], v[18:19], v[34:35]
	v_cvt_f32_f64_e32 v45, v[26:27]
	v_mul_f64 v[26:27], v[16:17], v[34:35]
	v_fma_f64 v[28:29], v[16:17], v[32:33], -v[36:37]
	v_fmac_f64_e32 v[26:27], v[18:19], v[32:33]
	v_cvt_f32_f64_e32 v44, v[28:29]
	v_cvt_f32_f64_e32 v46, v[26:27]
	global_store_dword v[22:23], v45, off offset:1024
	global_store_dword v[22:23], v43, off offset:1280
	global_store_dword v[22:23], v44, off offset:1536
	global_store_dword v[22:23], v46, off offset:1792
	v_mov_b32_e32 v26, v104
	v_mov_b32_e32 v27, v105
	v_mov_b32_e32 v28, v106
	v_mov_b32_e32 v29, v107
	v_cvt_f64_f32_e32 v[32:33], v27
	v_cvt_f64_f32_e32 v[34:35], v29
	v_cvt_f64_f32_e32 v[28:29], v28
	v_cvt_f64_f32_e32 v[26:27], v26
	v_mul_f64 v[36:37], v[16:17], v[28:29]
	v_mul_f64 v[28:29], v[18:19], v[28:29]
	v_fmac_f64_e32 v[36:37], v[18:19], v[26:27]
	v_fma_f64 v[26:27], v[16:17], v[26:27], -v[28:29]
	v_cvt_f32_f64_e32 v47, v[36:37]
	v_mul_f64 v[36:37], v[18:19], v[34:35]
	v_cvt_f32_f64_e32 v49, v[26:27]
	v_mul_f64 v[26:27], v[16:17], v[34:35]
	v_fma_f64 v[28:29], v[16:17], v[32:33], -v[36:37]
	v_fmac_f64_e32 v[26:27], v[18:19], v[32:33]
	v_cvt_f32_f64_e32 v48, v[28:29]
	v_cvt_f32_f64_e32 v50, v[26:27]
	global_store_dword v[22:23], v49, off offset:2048
	global_store_dword v[22:23], v47, off offset:2304
	global_store_dword v[22:23], v48, off offset:2560
	global_store_dword v[22:23], v50, off offset:2816
	v_mov_b32_e32 v26, v108
	v_mov_b32_e32 v27, v109
	v_mov_b32_e32 v28, v110
	v_mov_b32_e32 v29, v111
	v_cvt_f64_f32_e32 v[32:33], v27
	v_cvt_f64_f32_e32 v[34:35], v29
	v_cvt_f64_f32_e32 v[28:29], v28
	v_cvt_f64_f32_e32 v[26:27], v26
	v_mul_f64 v[36:37], v[16:17], v[28:29]
	v_mul_f64 v[28:29], v[18:19], v[28:29]
	v_mul_f64 v[38:39], v[18:19], v[34:35]
	v_mul_f64 v[34:35], v[16:17], v[34:35]
	v_fmac_f64_e32 v[36:37], v[18:19], v[26:27]
	v_fma_f64 v[26:27], v[16:17], v[26:27], -v[28:29]
	v_fma_f64 v[28:29], v[16:17], v[32:33], -v[38:39]
	v_fmac_f64_e32 v[34:35], v[18:19], v[32:33]
	v_cvt_f32_f64_e32 v53, v[26:27]
	v_cvt_f32_f64_e32 v51, v[36:37]
	v_cvt_f32_f64_e32 v52, v[28:29]
	v_cvt_f32_f64_e32 v54, v[34:35]
	global_store_dword v[22:23], v53, off offset:3072
	global_store_dword v[22:23], v51, off offset:3328
	global_store_dword v[22:23], v52, off offset:3584
	global_store_dword v[22:23], v54, off offset:3840
	v_mov_b32_e32 v26, v112
	v_mov_b32_e32 v27, v113
	v_mov_b32_e32 v28, v114
	v_mov_b32_e32 v29, v115
	v_add_co_u32_e32 v22, vcc, s6, v22
	s_movk_i32 s6, 0x1fff
	s_nop 0
	v_addc_co_u32_e32 v23, vcc, 0, v23, vcc
	v_cmp_lt_i32_e32 vcc, s6, v3
	s_or_b64 s[26:27], vcc, s[26:27]
	v_cvt_f64_f32_e32 v[32:33], v27
	v_cvt_f64_f32_e32 v[34:35], v29
	v_cvt_f64_f32_e32 v[28:29], v28
	v_cvt_f64_f32_e32 v[26:27], v26
	v_mul_f64 v[36:37], v[16:17], v[28:29]
	v_mul_f64 v[28:29], v[18:19], v[28:29]
	v_mul_f64 v[38:39], v[18:19], v[34:35]
	v_mul_f64 v[34:35], v[16:17], v[34:35]
	v_fmac_f64_e32 v[36:37], v[18:19], v[26:27]
	v_fma_f64 v[26:27], v[16:17], v[26:27], -v[28:29]
	v_fma_f64 v[28:29], v[16:17], v[32:33], -v[38:39]
	v_fmac_f64_e32 v[34:35], v[18:19], v[32:33]
	v_cvt_f32_f64_e32 v57, v[26:27]
	v_cvt_f32_f64_e32 v55, v[36:37]
	v_cvt_f32_f64_e32 v56, v[28:29]
	v_cvt_f32_f64_e32 v58, v[34:35]
	global_store_dword v[22:23], v57, off
	global_store_dword v[22:23], v55, off offset:256
	global_store_dword v[22:23], v56, off offset:512
	global_store_dword v[22:23], v58, off offset:768
	v_mov_b32_e32 v26, v116
	v_mov_b32_e32 v27, v117
	v_mov_b32_e32 v28, v118
	v_mov_b32_e32 v29, v119
	v_cvt_f64_f32_e32 v[32:33], v27
	v_cvt_f64_f32_e32 v[34:35], v29
	v_cvt_f64_f32_e32 v[28:29], v28
	v_cvt_f64_f32_e32 v[26:27], v26
	v_mul_f64 v[36:37], v[16:17], v[28:29]
	v_mul_f64 v[28:29], v[18:19], v[28:29]
	v_mul_f64 v[38:39], v[18:19], v[34:35]
	v_mul_f64 v[34:35], v[16:17], v[34:35]
	v_fmac_f64_e32 v[36:37], v[18:19], v[26:27]
	v_fma_f64 v[26:27], v[16:17], v[26:27], -v[28:29]
	v_fma_f64 v[28:29], v[16:17], v[32:33], -v[38:39]
	v_fmac_f64_e32 v[34:35], v[18:19], v[32:33]
	v_cvt_f32_f64_e32 v61, v[26:27]
	v_cvt_f32_f64_e32 v59, v[36:37]
	v_cvt_f32_f64_e32 v60, v[28:29]
	v_cvt_f32_f64_e32 v62, v[34:35]
	global_store_dword v[22:23], v61, off offset:1024
	global_store_dword v[22:23], v59, off offset:1280
	global_store_dword v[22:23], v60, off offset:1536
	global_store_dword v[22:23], v62, off offset:1792
	v_mov_b32_e32 v26, v120
; __device__ __forceinline__ unsigned pk2(float lo, float hi) { f32x2 v = {lo, hi}; bf16x2_t b = __builtin_convertvector(v, bf16x2_t); return __builtin_bit_cast(unsigned, b); }
; #define FIN(i) ((const float*)(const GAS float*)(((const float* const __attribute__((address_space(4)))*)__builtin_amdgcn_kernarg_segment_ptr())[i]))
; __device__ __forceinline__ void phase_prologue(Frame& F) {
;     ...
;         for (int c = 0; c < 16; c += 2) { const double br0 = bre[c], bi0 = bim[c], br1 = bre[c + 1], bi1 = bim[c + 1];
;             const float r0 = (float)(cr * br0 - ci * bi0), i0 = (float)(cr * bi0 + ci * br0), r1 = (float)(cr * br1 - ci * bi1), i1 = (float)(cr * bi1 + ci * br1);
;             bb[c * 128 + n] = r0; bb[c * 128 + 64 + n] = i0; bb[(c + 1) * 128 + n] = r1; bb[(c + 1) * 128 + 64 + n] = i1;
;             bb16[(((g * 2 + 0) * 64 + n) * 16 + c) >> 1] = pk2(r0, r1); bb16[(((g * 2 + 1) * 64 + n) * 16 + c) >> 1] = pk2(i0, i1); }
;         bf16_t* cm = (bf16_t*)(F.ws + WS_SCM + l * al1m(SZ_SCM)) + (size_t)g * 16 * 128;
;         const float* cre = FIN(IN_CRE) + (size_t)(l * 64 + g) * 16 * 64; const float* cim = FIN(IN_CIM) + (size_t)(l * 64 + g) * 16 * 64;
;         for (int c = 0; c < 16; ++c) *(unsigned*)(cm + c * 128 + 2 * n) = pk2(cre[c * 64 + n], -cim[c * 64 + n]);
	v_mov_b32_e32 v27, v121
	v_mov_b32_e32 v28, v122
	v_mov_b32_e32 v29, v123
	v_cvt_f64_f32_e32 v[32:33], v27
	v_cvt_f64_f32_e32 v[34:35], v29
	v_cvt_f64_f32_e32 v[28:29], v28
	v_cvt_f64_f32_e32 v[26:27], v26
	v_mul_f64 v[36:37], v[16:17], v[28:29]
	v_mul_f64 v[28:29], v[18:19], v[28:29]
	v_mul_f64 v[38:39], v[18:19], v[34:35]
	v_mul_f64 v[34:35], v[16:17], v[34:35]
	v_fmac_f64_e32 v[36:37], v[18:19], v[26:27]
	v_fma_f64 v[26:27], v[16:17], v[26:27], -v[28:29]
	v_fma_f64 v[28:29], v[16:17], v[32:33], -v[38:39]
	v_fmac_f64_e32 v[34:35], v[18:19], v[32:33]
	v_cvt_f32_f64_e32 v63, v[26:27]
	v_cvt_f32_f64_e32 v38, v[36:37]
	v_cvt_f32_f64_e32 v39, v[28:29]
	v_cvt_f32_f64_e32 v64, v[34:35]
	global_store_dword v[22:23], v63, off offset:2048
	global_store_dword v[22:23], v38, off offset:2304
	global_store_dword v[22:23], v39, off offset:2560
	global_store_dword v[22:23], v64, off offset:2816
	v_mov_b32_e32 v20, v124
	v_mov_b32_e32 v21, v125
	s_nop 0
	v_mov_b32_e32 v24, v126
	v_mov_b32_e32 v25, v127
	v_lshl_add_u64 v[26:27], v[6:7], 0, v[12:13]
	v_lshl_add_u64 v[12:13], v[8:9], 0, v[12:13]
	v_cvt_f64_f32_e32 v[28:29], v21
	v_cvt_f64_f32_e32 v[32:33], v25
	v_cvt_f64_f32_e32 v[24:25], v24
	v_cvt_f64_f32_e32 v[20:21], v20
	v_mul_f64 v[34:35], v[16:17], v[24:25]
	v_mul_f64 v[24:25], v[18:19], v[24:25]
	v_mul_f64 v[36:37], v[18:19], v[32:33]
	v_mul_f64 v[32:33], v[16:17], v[32:33]
	v_fmac_f64_e32 v[34:35], v[18:19], v[20:21]
	v_fma_f64 v[20:21], v[16:17], v[20:21], -v[24:25]
	v_fma_f64 v[16:17], v[16:17], v[28:29], -v[36:37]
	v_fmac_f64_e32 v[32:33], v[18:19], v[28:29]
	v_cvt_f32_f64_e32 v28, v[20:21]
	v_cvt_f32_f64_e32 v24, v[34:35]
	v_cvt_f32_f64_e32 v25, v[16:17]
	v_cvt_f32_f64_e32 v29, v[32:33]
	global_store_dword v[22:23], v28, off offset:3072
	global_store_dword v[22:23], v24, off offset:3328
	global_store_dword v[22:23], v25, off offset:3584
	global_store_dword v[22:23], v29, off offset:3840
	global_load_dword v32, v[12:13], off
	global_load_dword v33, v[12:13], off offset:256
	global_load_dword v34, v[12:13], off offset:512
	global_load_dword v35, v[12:13], off offset:768
	global_load_dword v36, v[12:13], off offset:1024
	global_load_dword v37, v[12:13], off offset:1280
	global_load_dword v65, v[12:13], off offset:1536
	global_load_dword v67, v[12:13], off offset:1792
	global_load_dword v69, v[12:13], off offset:2048
	global_load_dword v70, v[12:13], off offset:2304
	global_load_dword v71, v[12:13], off offset:2560
	global_load_dword v72, v[12:13], off offset:2816
	global_load_dword v73, v[12:13], off offset:3072
	global_load_dword v74, v[12:13], off offset:3328
	global_load_dword v75, v[12:13], off offset:3584
	global_load_dword v76, v[12:13], off offset:3840
	global_load_dword v77, v[26:27], off
	global_load_dword v78, v[26:27], off offset:256
	global_load_dword v79, v[26:27], off offset:512
	global_load_dword v80, v[26:27], off offset:768
	global_load_dword v81, v[26:27], off offset:1024
	global_load_dword v82, v[26:27], off offset:1280
	global_load_dword v83, v[26:27], off offset:1536
	global_load_dword v84, v[26:27], off offset:1792
	global_load_dword v85, v[26:27], off offset:2048
	global_load_dword v86, v[26:27], off offset:2304
	global_load_dword v87, v[26:27], off offset:2560
	global_load_dword v88, v[26:27], off offset:2816
	global_load_dword v89, v[26:27], off offset:3072
	global_load_dword v90, v[26:27], off offset:3328
	global_load_dword v91, v[26:27], off offset:3584
	s_nop 0
	global_load_dword v26, v[26:27], off offset:3840
	v_lshlrev_b32_e32 v12, 12, v11
	v_mov_b32_e32 v13, v5
	v_lshl_add_u64 v[16:17], s[38:39], 0, v[14:15]
	v_lshl_add_u64 v[14:15], s[40:41], 0, v[14:15]
	v_mov_b32_e32 v11, v5
	v_lshl_add_u64 v[14:15], v[14:15], 0, v[12:13]
	v_lshl_or_b32 v4, v2, 1, v12
	v_lshl_add_u64 v[20:21], v[14:15], 0, v[10:11]
	v_lshl_add_u64 v[22:23], v[16:17], 0, v[4:5]
	v_cvt_pk_bf16_f32 v12, v41, v40
	v_cvt_pk_bf16_f32 v16, v31, v42
	v_cvt_pk_bf16_f32 v13, v45, v44
	v_cvt_pk_bf16_f32 v17, v43, v46
	v_cvt_pk_bf16_f32 v14, v49, v48
	v_cvt_pk_bf16_f32 v18, v47, v50
	v_cvt_pk_bf16_f32 v15, v53, v52
	v_cvt_pk_bf16_f32 v19, v51, v54
	global_store_dwordx4 v[22:23], v[12:15], off
	global_store_dwordx4 v[22:23], v[16:19], off offset:2048
	s_waitcnt vmcnt(33)
; __device__ __forceinline__ unsigned pk2(float lo, float hi) { f32x2 v = {lo, hi}; bf16x2_t b = __builtin_convertvector(v, bf16x2_t); return __builtin_bit_cast(unsigned, b); }
; #define FIN(i) ((const float*)(const GAS float*)(((const float* const __attribute__((address_space(4)))*)__builtin_amdgcn_kernarg_segment_ptr())[i]))
; __device__ __forceinline__ void phase_prologue(Frame& F) {
;     ...
;         bf16_t* cm = (bf16_t*)(F.ws + WS_SCM + l * al1m(SZ_SCM)) + (size_t)g * 16 * 128;
;         const float* cre = FIN(IN_CRE) + (size_t)(l * 64 + g) * 16 * 64; const float* cim = FIN(IN_CIM) + (size_t)(l * 64 + g) * 16 * 64;
;         for (int c = 0; c < 16; ++c) *(unsigned*)(cm + c * 128 + 2 * n) = pk2(cre[c * 64 + n], -cim[c * 64 + n]);
	v_xor_b32_e32 v4, 0x80000000, v32
	v_cvt_pk_bf16_f32 v12, v57, v56
	v_cvt_pk_bf16_f32 v16, v55, v58
	v_cvt_pk_bf16_f32 v13, v61, v60
	v_cvt_pk_bf16_f32 v17, v59, v62
	v_cvt_pk_bf16_f32 v14, v63, v39
	v_cvt_pk_bf16_f32 v18, v38, v64
	v_cvt_pk_bf16_f32 v15, v28, v25
	v_cvt_pk_bf16_f32 v19, v24, v29
	global_store_dwordx4 v[22:23], v[12:15], off offset:16
	global_store_dwordx4 v[22:23], v[16:19], off offset:2064
	s_waitcnt vmcnt(34)
	v_xor_b32_e32 v11, 0x80000000, v33
	s_waitcnt vmcnt(33)
	v_xor_b32_e32 v12, 0x80000000, v34
	s_waitcnt vmcnt(32)
	v_xor_b32_e32 v13, 0x80000000, v35
	s_waitcnt vmcnt(31)
	v_xor_b32_e32 v14, 0x80000000, v36
	s_waitcnt vmcnt(30)
	v_xor_b32_e32 v15, 0x80000000, v37
	s_waitcnt vmcnt(29)
	v_xor_b32_e32 v16, 0x80000000, v65
	s_waitcnt vmcnt(28)
	v_xor_b32_e32 v17, 0x80000000, v67
	s_waitcnt vmcnt(27)
	v_xor_b32_e32 v18, 0x80000000, v69
	s_waitcnt vmcnt(26)
	v_xor_b32_e32 v19, 0x80000000, v70
	s_waitcnt vmcnt(25)
	v_xor_b32_e32 v22, 0x80000000, v71
	s_waitcnt vmcnt(24)
	v_xor_b32_e32 v23, 0x80000000, v72
	s_waitcnt vmcnt(23)
	v_xor_b32_e32 v24, 0x80000000, v73
	s_waitcnt vmcnt(22)
	v_xor_b32_e32 v25, 0x80000000, v74
	s_waitcnt vmcnt(21)
	v_xor_b32_e32 v27, 0x80000000, v75
	s_waitcnt vmcnt(20)
	v_xor_b32_e32 v28, 0x80000000, v76
	s_waitcnt vmcnt(19)
	v_cvt_pk_bf16_f32 v4, v77, v4
	s_waitcnt vmcnt(18)
	v_cvt_pk_bf16_f32 v11, v78, v11
	s_waitcnt vmcnt(17)
	v_cvt_pk_bf16_f32 v12, v79, v12
	s_waitcnt vmcnt(16)
	v_cvt_pk_bf16_f32 v13, v80, v13
	s_waitcnt vmcnt(15)
	v_cvt_pk_bf16_f32 v14, v81, v14
	s_waitcnt vmcnt(14)
	v_cvt_pk_bf16_f32 v15, v82, v15
	s_waitcnt vmcnt(13)
	v_cvt_pk_bf16_f32 v16, v83, v16
	s_waitcnt vmcnt(12)
	v_cvt_pk_bf16_f32 v17, v84, v17
	s_waitcnt vmcnt(11)
	v_cvt_pk_bf16_f32 v18, v85, v18
	s_waitcnt vmcnt(10)
	v_cvt_pk_bf16_f32 v19, v86, v19
	s_waitcnt vmcnt(9)
	v_cvt_pk_bf16_f32 v22, v87, v22
	s_waitcnt vmcnt(8)
	v_cvt_pk_bf16_f32 v23, v88, v23
	s_waitcnt vmcnt(7)
	v_cvt_pk_bf16_f32 v24, v89, v24
	s_waitcnt vmcnt(6)
	v_cvt_pk_bf16_f32 v25, v90, v25
	s_waitcnt vmcnt(5)
	v_cvt_pk_bf16_f32 v27, v91, v27
	s_waitcnt vmcnt(4)
	v_cvt_pk_bf16_f32 v26, v26, v28
	global_store_dword v[20:21], v4, off
	global_store_dword v[20:21], v11, off offset:256
	global_store_dword v[20:21], v12, off offset:512
	global_store_dword v[20:21], v13, off offset:768
	global_store_dword v[20:21], v14, off offset:1024
	global_store_dword v[20:21], v15, off offset:1280
	global_store_dword v[20:21], v16, off offset:1536
	global_store_dword v[20:21], v17, off offset:1792
	global_store_dword v[20:21], v18, off offset:2048
	global_store_dword v[20:21], v19, off offset:2304
	global_store_dword v[20:21], v22, off offset:2560
	global_store_dword v[20:21], v23, off offset:2816
	global_store_dword v[20:21], v24, off offset:3072
	global_store_dword v[20:21], v25, off offset:3328
	global_store_dword v[20:21], v27, off offset:3584
	global_store_dword v[20:21], v26, off offset:3840
	s_andn2_b64 exec, exec, s[26:27]
	s_cbranch_execz .LBB0_83
